# kind-1 GEMM bf16 epilogue writes whole 128-byte lines: weight rows staged so a wave owns 64 adjacent columns + row_ror:8 lane exchange (8 rows x 128 B per store)
# baseline (speedup 1.0000x reference)
.LBB0_657:
	v_readlane_b32 s4, v255, 10
	v_readlane_b32 s5, v255, 11
	s_xor_b64 s[4:5], s[4:5], -1
	s_andn2_b64 vcc, exec, s[0:1]
	s_cbranch_vccnz .LBB0_715
	s_waitcnt lgkmcnt(0)
	v_bfe_i32 v2, v12, 27, 1
	v_lshlrev_b32_e32 v0, 4, v12
	v_lshrrev_b32_e32 v2, 22, v2
	v_add_u32_e32 v2, v0, v2
	v_and_b32_e32 v2, 0xfffffc00, v2
	v_ashrrev_i32_e32 v1, 31, v12
	v_sub_u32_e32 v2, v0, v2
	v_lshrrev_b32_e32 v1, 26, v1
	v_lshrrev_b32_e32 v3, 4, v2
	v_add_u32_e32 v1, v12, v1
	v_bitop3_b32 v3, v3, v2, 32 bitop3:0x6c
	v_ashrrev_i32_e32 v2, 31, v2
	v_ashrrev_i32_e32 v1, 6, v1
	v_lshrrev_b32_e32 v2, 26, v2
	v_lshlrev_b32_e32 v4, 3, v1
	v_add_u32_e32 v2, v3, v2
	v_and_b32_e32 v4, -16, v4
	v_ashrrev_i32_e32 v2, 6, v2
	v_lshlrev_b32_e32 v1, 5, v1
	v_add_u32_e32 v4, v2, v4
	v_and_b32_e32 v13, 32, v1
	v_mul_i32_i24_e32 v1, 64, v2
	v_sub_u32_e32 v1, v3, v1
	v_lshlrev_b32_e32 v3, 1, v4
	v_lshrrev_b32_e32 v5, 2, v4
	v_and_b32_e32 v2, 3, v2
	s_mov_b32 s1, 0x7fffffe0
	v_ashrrev_i16_sdwa v1, v173, sext(v1) dst_sel:DWORD dst_unused:UNUSED_PAD src0_sel:DWORD src1_sel:BYTE_0
	v_and_b32_e32 v3, 24, v3
	v_and_b32_e32 v5, 4, v5
	v_and_or_b32 v2, v4, s1, v2
	v_bfe_i32 v14, v1, 0, 16
	v_or3_b32 v2, v2, v5, v3
	v_readlane_b32 s16, v255, 6
	v_add_u32_e32 v1, v13, v14
	v_add_u32_e32 v0, 0x2000, v0
	v_mul_lo_u32 v15, v4, s16
	v_and_b32_e32 v20, 0x60, v2
	v_add_u32_e32 v2, v2, v20
	v_mul_lo_u32 v2, v2, s16
	v_add_lshl_u32 v132, v1, v15, 1
	v_add_lshl_u32 v134, v2, v1, 1
	v_ashrrev_i32_e32 v1, 31, v0
	v_lshrrev_b32_e32 v1, 22, v1
	v_add_u32_e32 v1, v0, v1
	v_ashrrev_i32_e32 v1, 10, v1
	v_mul_i32_i24_e32 v2, 0x400, v1
	v_sub_u32_e32 v0, v0, v2
	v_lshrrev_b32_e32 v2, 4, v0
	v_bitop3_b32 v0, v2, v0, 32 bitop3:0x6c
	v_ashrrev_i32_e32 v3, 31, v0
	v_lshrrev_b32_e32 v3, 26, v3
	v_lshlrev_b32_e32 v2, 3, v1
	v_add_u32_e32 v3, v0, v3
	v_and_b32_e32 v2, -16, v2
	v_ashrrev_i32_e32 v4, 6, v3
	v_lshlrev_b32_e32 v1, 5, v1
	v_add_u32_e32 v2, v4, v2
	v_and_b32_e32 v16, 32, v1
	v_and_b32_e32 v1, 0xc0, v3
	s_lshl_b32 s10, s16, 8
	s_lshl_b32 s100, s16, 6
	s_mov_b32 s11, s80
	v_sub_u32_e32 v0, v0, v1
	v_lshlrev_b32_e32 v1, 1, v2
	v_lshrrev_b32_e32 v3, 2, v2
	v_and_b32_e32 v4, 3, v4
	s_lshl_b64 s[12:13], s[10:11], 1
	s_ashr_i32 s14, s53, 31
	v_and_b32_e32 v1, 24, v1
	v_and_b32_e32 v3, 4, v3
	v_and_or_b32 v4, v2, s1, v4
	s_mul_i32 s14, s12, s14
	s_mul_hi_u32 s15, s12, s53
	v_or3_b32 v1, v4, v3, v1
	s_add_i32 s14, s15, s14
	s_bfe_u32 s15, s16, 0x10017
	v_mul_lo_u32 v18, v2, s16
	v_and_b32_e32 v20, 0x60, v1
	v_add_u32_e32 v1, v1, v20
	v_mul_lo_u32 v1, v1, s16
	s_mul_i32 s16, s15, s53
	s_add_i32 s16, s14, s16
	s_ashr_i32 s14, s52, 31
	s_mul_i32 s14, s12, s14
	s_mul_hi_u32 s18, s12, s52
	s_ashr_i32 s1, s3, 6
	s_add_i32 s14, s18, s14
	s_mul_i32 s15, s15, s52
	s_ashr_i32 s0, s3, 8
	s_lshl_b32 s26, s1, 10
	s_add_i32 s14, s14, s15
	s_mul_i32 s15, s12, s52
	v_readlane_b32 s18, v255, 7
	v_readlane_b32 s19, v255, 8
	s_add_u32 s22, s18, s15
	v_ashrrev_i16_sdwa v0, v173, sext(v0) dst_sel:DWORD dst_unused:UNUSED_PAD src0_sel:DWORD src1_sel:BYTE_0
	s_addc_u32 s23, s19, s14
	s_add_i32 s27, s26, 0x100
	v_bfe_i32 v17, v0, 0, 16
	s_add_i32 m0, s27, 0x10000
	v_add_u32_e32 v0, v16, v17
	global_load_lds_dwordx4 v134, s[22:23]
	s_add_i32 m0, s27, 0x12000
	v_add_lshl_u32 v138, v1, v0, 1
	s_add_u32 s14, s22, s100
	global_load_lds_dwordx4 v138, s[22:23]
	s_addc_u32 s15, s23, 0
	s_add_i32 m0, s27, 0x14000
	s_mul_i32 s17, s12, s53
	global_load_lds_dwordx4 v134, s[14:15]
	s_add_i32 m0, s27, 0x16000
	v_readlane_b32 s18, v255, 2
	v_readlane_b32 s19, v255, 3
	s_add_u32 s20, s18, s17
	s_addc_u32 s21, s19, s16
	s_add_i32 s35, s27, 0x2000
	global_load_lds_dwordx4 v138, s[14:15]
	s_mov_b32 m0, s27
	s_add_u32 s16, s20, s10
	v_add_lshl_u32 v136, v0, v18, 1
	global_load_lds_dwordx4 v132, s[20:21]
	s_mov_b32 m0, s35
	s_addc_u32 s17, s21, 0
	s_add_i32 s40, s27, 0x4000
	global_load_lds_dwordx4 v136, s[20:21]
	s_mov_b32 m0, s40
	s_add_i32 s41, s27, 0x6000
	global_load_lds_dwordx4 v132, s[16:17]
	s_mov_b32 m0, s41
	v_mov_b32_e32 v135, v113
	global_load_lds_dwordx4 v136, s[16:17]
	v_mov_b32_e32 v139, v113
	v_mov_b32_e32 v133, v113
	v_mov_b32_e32 v137, v113
	s_cmp_eq_u32 s0, 1
	v_lshl_add_u64 v[8:9], s[22:23], 0, v[134:135]
	v_lshl_add_u64 v[4:5], s[22:23], 0, v[138:139]
	v_lshl_add_u64 v[2:3], s[14:15], 0, v[134:135]
	v_lshl_add_u64 v[0:1], s[14:15], 0, v[138:139]
	v_lshl_add_u64 v[6:7], s[20:21], 0, v[132:133]
	s_cselect_b64 s[14:15], -1, 0
	s_cmp_lg_u32 s0, 1
	v_lshl_add_u64 v[10:11], s[20:21], 0, v[136:137]
	s_cbranch_scc1 .LBB0_660
	s_barrier

.LBB0_675:
	s_add_i32 s54, s22, 2
	s_add_u32 s55, s20, 0x80
	s_addc_u32 s23, s21, 0
	s_add_i32 s58, s33, 0x100
	s_cmp_eq_u32 s44, s22
	s_cselect_b32 s23, s1, s23
	s_cselect_b32 s22, s0, s55
	v_add_u32_e32 v112, s58, v147
	s_cselect_b32 s57, s19, s39
	s_cselect_b32 s56, s18, s38
	s_add_i32 s55, s29, 0x100
	ds_read_b128 v[150:153], v112
	ds_read_b128 v[190:193], v112 offset:1024
	ds_read_b128 v[194:197], v112 offset:2048
	ds_read_b128 v[198:201], v112 offset:3072
	v_add_u32_e32 v112, s55, v147
	ds_read_b128 v[202:205], v112
	ds_read_b128 v[206:209], v112 offset:1024
	ds_read_b128 v[210:213], v112 offset:2048
	ds_read_b128 v[214:217], v112 offset:3072
	v_lshl_add_u64 v[114:115], s[20:21], 0, v[140:141]
	s_add_i32 m0, s27, 0xc000
	ds_read_b128 v[218:221], v149
	ds_read_b128 v[222:225], v149 offset:1024
	ds_read_b128 v[226:229], v149 offset:2048
	ds_read_b128 v[230:233], v149 offset:3072
	ds_read_b128 v[234:237], v149 offset:4096
	ds_read_b128 v[238:241], v149 offset:5120
	ds_read_b128 v[242:245], v149 offset:6144
	ds_read_b128 v[246:249], v149 offset:7168
	global_load_lds_dwordx4 v[114:115], off
	v_lshl_add_u64 v[114:115], s[20:21], 0, v[142:143]
	s_add_i32 m0, s27, 0xe000
	s_nop 0
	global_load_lds_dwordx4 v[114:115], off
	s_waitcnt vmcnt(8)
	s_waitcnt lgkmcnt(0)
	s_barrier
	s_setprio 1
	s_waitcnt lgkmcnt(0)
	v_mfma_f32_16x16x32_bf16 v[128:131], v[150:153], v[218:221], v[128:131]
	v_mfma_f32_16x16x32_bf16 v[124:127], v[194:197], v[218:221], v[124:127]
	v_mfma_f32_16x16x32_bf16 v[108:111], v[150:153], v[226:229], v[108:111]
	v_mfma_f32_16x16x32_bf16 v[104:107], v[194:197], v[226:229], v[104:107]
	v_mfma_f32_16x16x32_bf16 v[92:95], v[150:153], v[234:237], v[92:95]
	v_mfma_f32_16x16x32_bf16 v[88:91], v[194:197], v[234:237], v[88:91]
	v_mfma_f32_16x16x32_bf16 v[76:79], v[150:153], v[242:245], v[76:79]
	v_mfma_f32_16x16x32_bf16 v[72:75], v[194:197], v[242:245], v[72:75]
	v_mfma_f32_16x16x32_bf16 v[128:131], v[190:193], v[222:225], v[128:131]
	v_mfma_f32_16x16x32_bf16 v[124:127], v[198:201], v[222:225], v[124:127]
	v_mfma_f32_16x16x32_bf16 v[108:111], v[190:193], v[230:233], v[108:111]
	v_mfma_f32_16x16x32_bf16 v[104:107], v[198:201], v[230:233], v[104:107]
	v_mfma_f32_16x16x32_bf16 v[92:95], v[190:193], v[238:241], v[92:95]
	v_mfma_f32_16x16x32_bf16 v[88:91], v[198:201], v[238:241], v[88:91]
	v_mfma_f32_16x16x32_bf16 v[76:79], v[190:193], v[246:249], v[76:79]
	v_mfma_f32_16x16x32_bf16 v[72:75], v[198:201], v[246:249], v[72:75]
	s_setprio 0
	s_setprio 1
	v_mfma_f32_16x16x32_bf16 v[120:123], v[202:205], v[218:221], v[120:123]
	v_mfma_f32_16x16x32_bf16 v[114:117], v[210:213], v[218:221], v[116:119]
	v_mfma_f32_16x16x32_bf16 v[100:103], v[202:205], v[226:229], v[100:103]
	v_mfma_f32_16x16x32_bf16 v[96:99], v[210:213], v[226:229], v[96:99]
	v_mfma_f32_16x16x32_bf16 v[84:87], v[202:205], v[234:237], v[84:87]
	v_mfma_f32_16x16x32_bf16 v[80:83], v[210:213], v[234:237], v[80:83]
	v_mfma_f32_16x16x32_bf16 v[68:71], v[202:205], v[242:245], v[68:71]
	v_mfma_f32_16x16x32_bf16 v[64:67], v[210:213], v[242:245], v[64:67]
	v_mfma_f32_16x16x32_bf16 v[120:123], v[206:209], v[222:225], v[120:123]
	v_mfma_f32_16x16x32_bf16 v[114:117], v[214:217], v[222:225], v[114:117]
	v_mfma_f32_16x16x32_bf16 v[100:103], v[206:209], v[230:233], v[100:103]
	v_mfma_f32_16x16x32_bf16 v[96:99], v[214:217], v[230:233], v[96:99]
	v_mfma_f32_16x16x32_bf16 v[84:87], v[206:209], v[238:241], v[84:87]
	v_mfma_f32_16x16x32_bf16 v[80:83], v[214:217], v[238:241], v[80:83]
	v_mfma_f32_16x16x32_bf16 v[68:71], v[206:209], v[246:249], v[68:71]
	v_mfma_f32_16x16x32_bf16 v[64:67], v[214:217], v[246:249], v[64:67]
	s_setprio 0
	s_barrier
	s_add_i32 s58, s58, s26
	v_lshl_add_u64 v[144:145], s[56:57], 0, v[134:135]
	s_mov_b32 m0, s58
	ds_read_b128 v[218:221], v149 offset:16384
	ds_read_b128 v[222:225], v149 offset:17408
	ds_read_b128 v[226:229], v149 offset:18432
	ds_read_b128 v[230:233], v149 offset:19456
	ds_read_b128 v[234:237], v149 offset:20480
	ds_read_b128 v[238:241], v149 offset:21504
	ds_read_b128 v[242:245], v149 offset:22528
	ds_read_b128 v[246:249], v149 offset:23552
	global_load_lds_dwordx4 v[144:145], off
	s_add_i32 m0, s58, 0x2000
	v_lshl_add_u64 v[154:155], s[56:57], 0, v[138:139]
	s_add_u32 s56, s56, s100
	s_addc_u32 s57, s57, 0
	s_add_i32 s55, s55, s26
	global_load_lds_dwordx4 v[154:155], off
	v_lshl_add_u64 v[170:171], s[56:57], 0, v[134:135]
	s_mov_b32 m0, s55
	v_lshl_add_u64 v[176:177], s[56:57], 0, v[138:139]
	global_load_lds_dwordx4 v[170:171], off
	s_add_i32 m0, s55, 0x2000
	v_lshl_add_u64 v[178:179], s[22:23], 0, v[132:133]
	global_load_lds_dwordx4 v[176:177], off
	s_mov_b32 m0, s27
	v_lshl_add_u64 v[180:181], s[22:23], 0, v[136:137]
	global_load_lds_dwordx4 v[178:179], off
	s_mov_b32 m0, s35
	s_nop 0
	global_load_lds_dwordx4 v[180:181], off
	s_waitcnt vmcnt(8)
	s_waitcnt lgkmcnt(0)
	s_barrier
	s_setprio 1
	s_waitcnt lgkmcnt(0)
	v_mfma_f32_16x16x32_bf16 v[60:63], v[150:153], v[218:221], v[60:63]
	v_mfma_f32_16x16x32_bf16 v[56:59], v[194:197], v[218:221], v[56:59]
	v_mfma_f32_16x16x32_bf16 v[44:47], v[150:153], v[226:229], v[44:47]
	v_mfma_f32_16x16x32_bf16 v[40:43], v[194:197], v[226:229], v[40:43]
	v_mfma_f32_16x16x32_bf16 v[28:31], v[150:153], v[234:237], v[28:31]
	v_mfma_f32_16x16x32_bf16 v[24:27], v[194:197], v[234:237], v[24:27]
	v_mfma_f32_16x16x32_bf16 v[12:15], v[150:153], v[242:245], v[12:15]
	v_mfma_f32_16x16x32_bf16 v[8:11], v[194:197], v[242:245], v[8:11]
	v_mfma_f32_16x16x32_bf16 v[60:63], v[190:193], v[222:225], v[60:63]
	v_mfma_f32_16x16x32_bf16 v[56:59], v[198:201], v[222:225], v[56:59]
	v_mfma_f32_16x16x32_bf16 v[44:47], v[190:193], v[230:233], v[44:47]
	v_mfma_f32_16x16x32_bf16 v[40:43], v[198:201], v[230:233], v[40:43]
	v_mfma_f32_16x16x32_bf16 v[28:31], v[190:193], v[238:241], v[28:31]
	v_mfma_f32_16x16x32_bf16 v[24:27], v[198:201], v[238:241], v[24:27]
	v_mfma_f32_16x16x32_bf16 v[12:15], v[190:193], v[246:249], v[12:15]
	v_mfma_f32_16x16x32_bf16 v[8:11], v[198:201], v[246:249], v[8:11]
	s_setprio 0
	s_setprio 1
	v_mfma_f32_16x16x32_bf16 v[52:55], v[202:205], v[218:221], v[52:55]
	v_mfma_f32_16x16x32_bf16 v[48:51], v[210:213], v[218:221], v[48:51]
	v_mfma_f32_16x16x32_bf16 v[36:39], v[202:205], v[226:229], v[36:39]
	v_mfma_f32_16x16x32_bf16 v[32:35], v[210:213], v[226:229], v[32:35]
	v_mfma_f32_16x16x32_bf16 v[20:23], v[202:205], v[234:237], v[20:23]
	v_mfma_f32_16x16x32_bf16 v[16:19], v[210:213], v[234:237], v[16:19]
	v_mfma_f32_16x16x32_bf16 v[4:7], v[202:205], v[242:245], v[4:7]
	v_mfma_f32_16x16x32_bf16 v[0:3], v[210:213], v[242:245], v[0:3]
	v_mfma_f32_16x16x32_bf16 v[52:55], v[206:209], v[222:225], v[52:55]
	v_mfma_f32_16x16x32_bf16 v[48:51], v[214:217], v[222:225], v[48:51]
	v_mfma_f32_16x16x32_bf16 v[36:39], v[206:209], v[230:233], v[36:39]
	v_mfma_f32_16x16x32_bf16 v[32:35], v[214:217], v[230:233], v[32:35]
	v_mfma_f32_16x16x32_bf16 v[20:23], v[206:209], v[238:241], v[20:23]
	v_mfma_f32_16x16x32_bf16 v[16:19], v[214:217], v[238:241], v[16:19]
	v_mfma_f32_16x16x32_bf16 v[4:7], v[206:209], v[246:249], v[4:7]
	v_mfma_f32_16x16x32_bf16 v[0:3], v[214:217], v[246:249], v[0:3]
	s_setprio 0
	s_barrier
	s_add_i32 s55, s8, 0x100
	v_add_u32_e32 v112, s55, v147
	s_add_i32 s56, s9, 0x100
	ds_read_b128 v[150:153], v112
	ds_read_b128 v[190:193], v112 offset:1024
	ds_read_b128 v[194:197], v112 offset:2048
	ds_read_b128 v[198:201], v112 offset:3072
	v_add_u32_e32 v112, s56, v147
	ds_read_b128 v[202:205], v112
	ds_read_b128 v[206:209], v112 offset:1024
	ds_read_b128 v[210:213], v112 offset:2048
	ds_read_b128 v[214:217], v112 offset:3072
	s_add_u32 s22, s22, s10
	s_addc_u32 s23, s23, 0
	s_mov_b32 m0, s40
	v_lshl_add_u64 v[118:119], s[22:23], 0, v[132:133]
	ds_read_b128 v[218:221], v149 offset:32768
	ds_read_b128 v[222:225], v149 offset:33792
	ds_read_b128 v[226:229], v149 offset:34816
	ds_read_b128 v[230:233], v149 offset:35840
	ds_read_b128 v[234:237], v149 offset:36864
	ds_read_b128 v[238:241], v149 offset:37888
	ds_read_b128 v[242:245], v149 offset:38912
	ds_read_b128 v[246:249], v149 offset:39936
	global_load_lds_dwordx4 v[118:119], off
	v_lshl_add_u64 v[118:119], s[22:23], 0, v[136:137]
	s_mov_b32 m0, s41
	s_nop 0
	global_load_lds_dwordx4 v[118:119], off
	s_waitcnt vmcnt(8)
	s_waitcnt lgkmcnt(0)
	s_barrier
	s_setprio 1
	s_waitcnt lgkmcnt(0)
	v_mfma_f32_16x16x32_bf16 v[128:131], v[150:153], v[218:221], v[128:131]
	v_mfma_f32_16x16x32_bf16 v[124:127], v[194:197], v[218:221], v[124:127]
	v_mfma_f32_16x16x32_bf16 v[108:111], v[150:153], v[226:229], v[108:111]
	v_mfma_f32_16x16x32_bf16 v[104:107], v[194:197], v[226:229], v[104:107]
	v_mfma_f32_16x16x32_bf16 v[92:95], v[150:153], v[234:237], v[92:95]
	v_mfma_f32_16x16x32_bf16 v[88:91], v[194:197], v[234:237], v[88:91]
	v_mfma_f32_16x16x32_bf16 v[76:79], v[150:153], v[242:245], v[76:79]
	v_mfma_f32_16x16x32_bf16 v[72:75], v[194:197], v[242:245], v[72:75]
	v_mfma_f32_16x16x32_bf16 v[128:131], v[190:193], v[222:225], v[128:131]
	v_mfma_f32_16x16x32_bf16 v[124:127], v[198:201], v[222:225], v[124:127]
	v_mfma_f32_16x16x32_bf16 v[108:111], v[190:193], v[230:233], v[108:111]
	v_mfma_f32_16x16x32_bf16 v[104:107], v[198:201], v[230:233], v[104:107]
	v_mfma_f32_16x16x32_bf16 v[92:95], v[190:193], v[238:241], v[92:95]
	v_mfma_f32_16x16x32_bf16 v[88:91], v[198:201], v[238:241], v[88:91]
	v_mfma_f32_16x16x32_bf16 v[76:79], v[190:193], v[246:249], v[76:79]
	v_mfma_f32_16x16x32_bf16 v[72:75], v[198:201], v[246:249], v[72:75]
	s_setprio 0
	s_setprio 1
	v_mfma_f32_16x16x32_bf16 v[118:121], v[202:205], v[218:221], v[120:123]
	v_mfma_f32_16x16x32_bf16 v[114:117], v[210:213], v[218:221], v[114:117]
	v_mfma_f32_16x16x32_bf16 v[100:103], v[202:205], v[226:229], v[100:103]
	v_mfma_f32_16x16x32_bf16 v[96:99], v[210:213], v[226:229], v[96:99]
	v_mfma_f32_16x16x32_bf16 v[84:87], v[202:205], v[234:237], v[84:87]
	v_mfma_f32_16x16x32_bf16 v[80:83], v[210:213], v[234:237], v[80:83]
	v_mfma_f32_16x16x32_bf16 v[68:71], v[202:205], v[242:245], v[68:71]
	v_mfma_f32_16x16x32_bf16 v[64:67], v[210:213], v[242:245], v[64:67]
	v_mfma_f32_16x16x32_bf16 v[120:123], v[206:209], v[222:225], v[118:121]
	v_mfma_f32_16x16x32_bf16 v[116:119], v[214:217], v[222:225], v[114:117]
	v_mfma_f32_16x16x32_bf16 v[100:103], v[206:209], v[230:233], v[100:103]
	v_mfma_f32_16x16x32_bf16 v[96:99], v[214:217], v[230:233], v[96:99]
	v_mfma_f32_16x16x32_bf16 v[84:87], v[206:209], v[238:241], v[84:87]
	v_mfma_f32_16x16x32_bf16 v[80:83], v[214:217], v[238:241], v[80:83]
	v_mfma_f32_16x16x32_bf16 v[68:71], v[206:209], v[246:249], v[68:71]
	v_mfma_f32_16x16x32_bf16 v[64:67], v[214:217], v[246:249], v[64:67]
	s_setprio 0
	s_barrier
	s_add_i32 s22, s55, s26
	v_lshl_add_u64 v[114:115], v[144:145], 0, s[30:31]
	s_mov_b32 m0, s22
	ds_read_b128 v[218:221], v149 offset:49152
	ds_read_b128 v[222:225], v149 offset:50176
	ds_read_b128 v[226:229], v149 offset:51200
	ds_read_b128 v[230:233], v149 offset:52224
	ds_read_b128 v[234:237], v149 offset:53248
	ds_read_b128 v[238:241], v149 offset:54272
	ds_read_b128 v[242:245], v149 offset:55296
	ds_read_b128 v[246:249], v149 offset:56320
	global_load_lds_dwordx4 v[114:115], off
	v_lshl_add_u64 v[114:115], v[154:155], 0, s[30:31]
	s_add_i32 m0, s22, 0x2000
	s_add_i32 s22, s56, s26
	global_load_lds_dwordx4 v[114:115], off
	v_lshl_add_u64 v[114:115], v[170:171], 0, s[30:31]
	s_mov_b32 m0, s22
	s_nop 0
	global_load_lds_dwordx4 v[114:115], off
	v_lshl_add_u64 v[114:115], v[176:177], 0, s[30:31]
	s_add_i32 m0, s22, 0x2000
	s_nop 0
	global_load_lds_dwordx4 v[114:115], off
	v_lshl_add_u64 v[114:115], v[178:179], 0, s[30:31]
	s_mov_b32 m0, s42
	s_nop 0
	global_load_lds_dwordx4 v[114:115], off
	v_lshl_add_u64 v[114:115], v[180:181], 0, s[30:31]
	s_mov_b32 m0, s43
	s_nop 0
	global_load_lds_dwordx4 v[114:115], off
	s_waitcnt vmcnt(8)
	s_waitcnt lgkmcnt(0)
	s_barrier
	s_setprio 1
	s_waitcnt lgkmcnt(0)
	v_mfma_f32_16x16x32_bf16 v[60:63], v[150:153], v[218:221], v[60:63]
	v_mfma_f32_16x16x32_bf16 v[56:59], v[194:197], v[218:221], v[56:59]
	v_mfma_f32_16x16x32_bf16 v[44:47], v[150:153], v[226:229], v[44:47]
	v_mfma_f32_16x16x32_bf16 v[40:43], v[194:197], v[226:229], v[40:43]
	v_mfma_f32_16x16x32_bf16 v[28:31], v[150:153], v[234:237], v[28:31]
	v_mfma_f32_16x16x32_bf16 v[24:27], v[194:197], v[234:237], v[24:27]
	v_mfma_f32_16x16x32_bf16 v[12:15], v[150:153], v[242:245], v[12:15]
	v_mfma_f32_16x16x32_bf16 v[8:11], v[194:197], v[242:245], v[8:11]
	v_mfma_f32_16x16x32_bf16 v[60:63], v[190:193], v[222:225], v[60:63]
	v_mfma_f32_16x16x32_bf16 v[56:59], v[198:201], v[222:225], v[56:59]
	v_mfma_f32_16x16x32_bf16 v[44:47], v[190:193], v[230:233], v[44:47]
	v_mfma_f32_16x16x32_bf16 v[40:43], v[198:201], v[230:233], v[40:43]
	v_mfma_f32_16x16x32_bf16 v[28:31], v[190:193], v[238:241], v[28:31]
	v_mfma_f32_16x16x32_bf16 v[24:27], v[198:201], v[238:241], v[24:27]
	v_mfma_f32_16x16x32_bf16 v[12:15], v[190:193], v[246:249], v[12:15]
	v_mfma_f32_16x16x32_bf16 v[8:11], v[198:201], v[246:249], v[8:11]
	s_setprio 0
	s_setprio 1
	v_mfma_f32_16x16x32_bf16 v[52:55], v[202:205], v[218:221], v[52:55]
	v_mfma_f32_16x16x32_bf16 v[48:51], v[210:213], v[218:221], v[48:51]
	v_mfma_f32_16x16x32_bf16 v[36:39], v[202:205], v[226:229], v[36:39]
	v_mfma_f32_16x16x32_bf16 v[32:35], v[210:213], v[226:229], v[32:35]
	v_mfma_f32_16x16x32_bf16 v[20:23], v[202:205], v[234:237], v[20:23]
	v_mfma_f32_16x16x32_bf16 v[16:19], v[210:213], v[234:237], v[16:19]
	v_mfma_f32_16x16x32_bf16 v[4:7], v[202:205], v[242:245], v[4:7]
	v_mfma_f32_16x16x32_bf16 v[0:3], v[210:213], v[242:245], v[0:3]
	v_mfma_f32_16x16x32_bf16 v[52:55], v[206:209], v[222:225], v[52:55]
	v_mfma_f32_16x16x32_bf16 v[48:51], v[214:217], v[222:225], v[48:51]
	v_mfma_f32_16x16x32_bf16 v[36:39], v[206:209], v[230:233], v[36:39]
	v_mfma_f32_16x16x32_bf16 v[32:35], v[214:217], v[230:233], v[32:35]
	v_mfma_f32_16x16x32_bf16 v[20:23], v[206:209], v[238:241], v[20:23]
	v_mfma_f32_16x16x32_bf16 v[16:19], v[214:217], v[238:241], v[16:19]
	v_mfma_f32_16x16x32_bf16 v[4:7], v[206:209], v[246:249], v[4:7]
	v_mfma_f32_16x16x32_bf16 v[0:3], v[214:217], v[246:249], v[0:3]
	s_setprio 0
	s_barrier
	s_add_u32 s20, s20, 0x100
	s_addc_u32 s21, s21, 0
	s_add_u32 s38, s38, 0x100
	s_addc_u32 s39, s39, 0
	s_cmp_ge_u32 s54, s34
	s_mov_b32 s22, s54
	s_cbranch_scc0 .LBB0_675
	s_and_b64 vcc, exec, s[16:17]
	s_cbranch_vccz .LBB0_678

.LBB0_678:
	v_lshl_add_u32 v112, s53, 8, v146
	v_and_b32_e32 v115, 0x60, v148
	v_lshl_or_b32 v114, s52, 8, v148
	v_add_u32_e32 v114, v114, v115
	v_and_b32_e32 v190, 8, v189
	v_mad_u32_u24 v144, v112, s6, v114
	s_lshl_b32 s20, s6, 1
	v_lshlrev_b32_e32 v144, 1, v144
	v_mul_lo_u32 v191, v190, s20
	s_lshl_b32 s21, s6, 4
	v_lshl_add_u32 v144, v190, 3, v144
	v_sub_u32_e32 v144, v144, v191
	v_add_u32_e32 v145, s21, v144
	s_andn2_b64 vcc, exec, s[4:5]
	s_cbranch_vccnz .Lg1e_norelu
	v_max_f32_e32 v0, 0, v0
	v_max_f32_e32 v1, 0, v1
	v_max_f32_e32 v2, 0, v2
	v_max_f32_e32 v3, 0, v3
	v_max_f32_e32 v4, 0, v4
	v_max_f32_e32 v5, 0, v5
	v_max_f32_e32 v6, 0, v6
	v_max_f32_e32 v7, 0, v7
	v_max_f32_e32 v8, 0, v8
	v_max_f32_e32 v9, 0, v9
	v_max_f32_e32 v10, 0, v10
	v_max_f32_e32 v11, 0, v11
	v_max_f32_e32 v12, 0, v12
	v_max_f32_e32 v13, 0, v13
	v_max_f32_e32 v14, 0, v14
	v_max_f32_e32 v15, 0, v15
	v_max_f32_e32 v16, 0, v16
	v_max_f32_e32 v17, 0, v17
	v_max_f32_e32 v18, 0, v18
	v_max_f32_e32 v19, 0, v19
	v_max_f32_e32 v20, 0, v20
	v_max_f32_e32 v21, 0, v21
	v_max_f32_e32 v22, 0, v22
	v_max_f32_e32 v23, 0, v23
	v_max_f32_e32 v24, 0, v24
	v_max_f32_e32 v25, 0, v25
	v_max_f32_e32 v26, 0, v26
	v_max_f32_e32 v27, 0, v27
	v_max_f32_e32 v28, 0, v28
	v_max_f32_e32 v29, 0, v29
	v_max_f32_e32 v30, 0, v30
	v_max_f32_e32 v31, 0, v31
	v_max_f32_e32 v32, 0, v32
	v_max_f32_e32 v33, 0, v33
	v_max_f32_e32 v34, 0, v34
	v_max_f32_e32 v35, 0, v35
	v_max_f32_e32 v36, 0, v36
	v_max_f32_e32 v37, 0, v37
	v_max_f32_e32 v38, 0, v38
	v_max_f32_e32 v39, 0, v39
	v_max_f32_e32 v40, 0, v40
	v_max_f32_e32 v41, 0, v41
	v_max_f32_e32 v42, 0, v42
	v_max_f32_e32 v43, 0, v43
	v_max_f32_e32 v44, 0, v44
	v_max_f32_e32 v45, 0, v45
	v_max_f32_e32 v46, 0, v46
	v_max_f32_e32 v47, 0, v47
	v_max_f32_e32 v48, 0, v48
	v_max_f32_e32 v49, 0, v49
	v_max_f32_e32 v50, 0, v50
	v_max_f32_e32 v51, 0, v51
	v_max_f32_e32 v52, 0, v52
	v_max_f32_e32 v53, 0, v53
	v_max_f32_e32 v54, 0, v54
	v_max_f32_e32 v55, 0, v55
	v_max_f32_e32 v56, 0, v56
	v_max_f32_e32 v57, 0, v57
	v_max_f32_e32 v58, 0, v58
	v_max_f32_e32 v59, 0, v59
	v_max_f32_e32 v60, 0, v60
	v_max_f32_e32 v61, 0, v61
	v_max_f32_e32 v62, 0, v62
	v_max_f32_e32 v63, 0, v63
	v_max_f32_e32 v64, 0, v64
	v_max_f32_e32 v65, 0, v65
	v_max_f32_e32 v66, 0, v66
	v_max_f32_e32 v67, 0, v67
	v_max_f32_e32 v68, 0, v68
	v_max_f32_e32 v69, 0, v69
	v_max_f32_e32 v70, 0, v70
	v_max_f32_e32 v71, 0, v71
	v_max_f32_e32 v72, 0, v72
	v_max_f32_e32 v73, 0, v73
	v_max_f32_e32 v74, 0, v74
	v_max_f32_e32 v75, 0, v75
	v_max_f32_e32 v76, 0, v76
	v_max_f32_e32 v77, 0, v77
	v_max_f32_e32 v78, 0, v78
	v_max_f32_e32 v79, 0, v79
	v_max_f32_e32 v80, 0, v80
	v_max_f32_e32 v81, 0, v81
	v_max_f32_e32 v82, 0, v82
	v_max_f32_e32 v83, 0, v83
	v_max_f32_e32 v84, 0, v84
	v_max_f32_e32 v85, 0, v85
	v_max_f32_e32 v86, 0, v86
	v_max_f32_e32 v87, 0, v87
	v_max_f32_e32 v88, 0, v88
	v_max_f32_e32 v89, 0, v89
	v_max_f32_e32 v90, 0, v90
	v_max_f32_e32 v91, 0, v91
	v_max_f32_e32 v92, 0, v92
	v_max_f32_e32 v93, 0, v93
	v_max_f32_e32 v94, 0, v94
	v_max_f32_e32 v95, 0, v95
	v_max_f32_e32 v96, 0, v96
	v_max_f32_e32 v97, 0, v97
	v_max_f32_e32 v98, 0, v98
	v_max_f32_e32 v99, 0, v99
	v_max_f32_e32 v100, 0, v100
	v_max_f32_e32 v101, 0, v101
	v_max_f32_e32 v102, 0, v102
	v_max_f32_e32 v103, 0, v103
	v_max_f32_e32 v104, 0, v104
	v_max_f32_e32 v105, 0, v105
	v_max_f32_e32 v106, 0, v106
	v_max_f32_e32 v107, 0, v107
	v_max_f32_e32 v108, 0, v108
	v_max_f32_e32 v109, 0, v109
	v_max_f32_e32 v110, 0, v110
	v_max_f32_e32 v111, 0, v111
	v_max_f32_e32 v116, 0, v116
	v_max_f32_e32 v117, 0, v117
	v_max_f32_e32 v118, 0, v118
	v_max_f32_e32 v119, 0, v119
	v_max_f32_e32 v120, 0, v120
	v_max_f32_e32 v121, 0, v121
	v_max_f32_e32 v122, 0, v122
	v_max_f32_e32 v123, 0, v123
	v_max_f32_e32 v124, 0, v124
	v_max_f32_e32 v125, 0, v125
	v_max_f32_e32 v126, 0, v126
	v_max_f32_e32 v127, 0, v127
	v_max_f32_e32 v128, 0, v128
	v_max_f32_e32 v129, 0, v129
	v_max_f32_e32 v130, 0, v130
	v_max_f32_e32 v131, 0, v131
	v_pk_mul_f32 v[0:1], v[0:1], v[0:1]
	v_pk_mul_f32 v[2:3], v[2:3], v[2:3]
	v_pk_mul_f32 v[4:5], v[4:5], v[4:5]
	v_pk_mul_f32 v[6:7], v[6:7], v[6:7]
	v_pk_mul_f32 v[8:9], v[8:9], v[8:9]
	v_pk_mul_f32 v[10:11], v[10:11], v[10:11]
	v_pk_mul_f32 v[12:13], v[12:13], v[12:13]
	v_pk_mul_f32 v[14:15], v[14:15], v[14:15]
	v_pk_mul_f32 v[16:17], v[16:17], v[16:17]
	v_pk_mul_f32 v[18:19], v[18:19], v[18:19]
	v_pk_mul_f32 v[20:21], v[20:21], v[20:21]
	v_pk_mul_f32 v[22:23], v[22:23], v[22:23]
	v_pk_mul_f32 v[24:25], v[24:25], v[24:25]
	v_pk_mul_f32 v[26:27], v[26:27], v[26:27]
	v_pk_mul_f32 v[28:29], v[28:29], v[28:29]
	v_pk_mul_f32 v[30:31], v[30:31], v[30:31]
	v_pk_mul_f32 v[32:33], v[32:33], v[32:33]
	v_pk_mul_f32 v[34:35], v[34:35], v[34:35]
	v_pk_mul_f32 v[36:37], v[36:37], v[36:37]
	v_pk_mul_f32 v[38:39], v[38:39], v[38:39]
	v_pk_mul_f32 v[40:41], v[40:41], v[40:41]
	v_pk_mul_f32 v[42:43], v[42:43], v[42:43]
	v_pk_mul_f32 v[44:45], v[44:45], v[44:45]
	v_pk_mul_f32 v[46:47], v[46:47], v[46:47]
	v_pk_mul_f32 v[48:49], v[48:49], v[48:49]
	v_pk_mul_f32 v[50:51], v[50:51], v[50:51]
	v_pk_mul_f32 v[52:53], v[52:53], v[52:53]
	v_pk_mul_f32 v[54:55], v[54:55], v[54:55]
	v_pk_mul_f32 v[56:57], v[56:57], v[56:57]
	v_pk_mul_f32 v[58:59], v[58:59], v[58:59]
	v_pk_mul_f32 v[60:61], v[60:61], v[60:61]
	v_pk_mul_f32 v[62:63], v[62:63], v[62:63]
	v_pk_mul_f32 v[64:65], v[64:65], v[64:65]
	v_pk_mul_f32 v[66:67], v[66:67], v[66:67]
	v_pk_mul_f32 v[68:69], v[68:69], v[68:69]
	v_pk_mul_f32 v[70:71], v[70:71], v[70:71]
	v_pk_mul_f32 v[72:73], v[72:73], v[72:73]
	v_pk_mul_f32 v[74:75], v[74:75], v[74:75]
	v_pk_mul_f32 v[76:77], v[76:77], v[76:77]
	v_pk_mul_f32 v[78:79], v[78:79], v[78:79]
	v_pk_mul_f32 v[80:81], v[80:81], v[80:81]
	v_pk_mul_f32 v[82:83], v[82:83], v[82:83]
	v_pk_mul_f32 v[84:85], v[84:85], v[84:85]
	v_pk_mul_f32 v[86:87], v[86:87], v[86:87]
	v_pk_mul_f32 v[88:89], v[88:89], v[88:89]
	v_pk_mul_f32 v[90:91], v[90:91], v[90:91]
	v_pk_mul_f32 v[92:93], v[92:93], v[92:93]
	v_pk_mul_f32 v[94:95], v[94:95], v[94:95]
	v_pk_mul_f32 v[96:97], v[96:97], v[96:97]
	v_pk_mul_f32 v[98:99], v[98:99], v[98:99]
	v_pk_mul_f32 v[100:101], v[100:101], v[100:101]
	v_pk_mul_f32 v[102:103], v[102:103], v[102:103]
	v_pk_mul_f32 v[104:105], v[104:105], v[104:105]
	v_pk_mul_f32 v[106:107], v[106:107], v[106:107]
	v_pk_mul_f32 v[108:109], v[108:109], v[108:109]
	v_pk_mul_f32 v[110:111], v[110:111], v[110:111]
	v_pk_mul_f32 v[116:117], v[116:117], v[116:117]
	v_pk_mul_f32 v[118:119], v[118:119], v[118:119]
	v_pk_mul_f32 v[120:121], v[120:121], v[120:121]
	v_pk_mul_f32 v[122:123], v[122:123], v[122:123]
	v_pk_mul_f32 v[124:125], v[124:125], v[124:125]
	v_pk_mul_f32 v[126:127], v[126:127], v[126:127]
	v_pk_mul_f32 v[128:129], v[128:129], v[128:129]
	v_pk_mul_f32 v[130:131], v[130:131], v[130:131]
.Lg1e_norelu:
	v_cvt_pk_bf16_f32 v128, v128, v129
	v_cvt_pk_bf16_f32 v129, v130, v131
	v_cvt_pk_bf16_f32 v130, v124, v125
	v_cvt_pk_bf16_f32 v131, v126, v127
	v_cvt_pk_bf16_f32 v120, v120, v121
	v_cvt_pk_bf16_f32 v121, v122, v123
	v_cvt_pk_bf16_f32 v122, v116, v117
	v_cvt_pk_bf16_f32 v123, v118, v119
	v_mov_b32_e32 v192, v128
	v_mov_b32_e32 v193, v129
	v_mov_b32_e32 v194, v130
	v_mov_b32_e32 v195, v131
	v_mov_b32_dpp v128, v120 row_ror:8 row_mask:0xf bank_mask:0xc
	v_mov_b32_dpp v129, v121 row_ror:8 row_mask:0xf bank_mask:0xc
	v_mov_b32_dpp v130, v122 row_ror:8 row_mask:0xf bank_mask:0xc
	v_mov_b32_dpp v131, v123 row_ror:8 row_mask:0xf bank_mask:0xc
	v_mov_b32_dpp v120, v192 row_ror:8 row_mask:0xf bank_mask:0x3
	v_mov_b32_dpp v121, v193 row_ror:8 row_mask:0xf bank_mask:0x3
	v_mov_b32_dpp v122, v194 row_ror:8 row_mask:0xf bank_mask:0x3
	v_mov_b32_dpp v123, v195 row_ror:8 row_mask:0xf bank_mask:0x3
	global_store_dwordx4 v144, v[128:131], s[24:25]
	global_store_dwordx4 v145, v[120:123], s[24:25]
	v_cvt_pk_bf16_f32 v108, v108, v109
	v_cvt_pk_bf16_f32 v109, v110, v111
	v_cvt_pk_bf16_f32 v110, v104, v105
	v_cvt_pk_bf16_f32 v111, v106, v107
	v_cvt_pk_bf16_f32 v100, v100, v101
	v_cvt_pk_bf16_f32 v101, v102, v103
	v_cvt_pk_bf16_f32 v102, v96, v97
	v_cvt_pk_bf16_f32 v103, v98, v99
	s_mul_i32 s20, s6, 32
	v_mov_b32_e32 v198, v108
	v_mov_b32_e32 v199, v109
	v_mov_b32_e32 v200, v110
	v_mov_b32_e32 v201, v111
	v_add_u32_e32 v202, s20, v144
	v_add_u32_e32 v203, s20, v145
	v_mov_b32_dpp v108, v100 row_ror:8 row_mask:0xf bank_mask:0xc
	v_mov_b32_dpp v109, v101 row_ror:8 row_mask:0xf bank_mask:0xc
	v_mov_b32_dpp v110, v102 row_ror:8 row_mask:0xf bank_mask:0xc
	v_mov_b32_dpp v111, v103 row_ror:8 row_mask:0xf bank_mask:0xc
	v_mov_b32_dpp v100, v198 row_ror:8 row_mask:0xf bank_mask:0x3
	v_mov_b32_dpp v101, v199 row_ror:8 row_mask:0xf bank_mask:0x3
	v_mov_b32_dpp v102, v200 row_ror:8 row_mask:0xf bank_mask:0x3
	v_mov_b32_dpp v103, v201 row_ror:8 row_mask:0xf bank_mask:0x3
	global_store_dwordx4 v202, v[108:111], s[24:25]
	global_store_dwordx4 v203, v[100:103], s[24:25]
	v_cvt_pk_bf16_f32 v92, v92, v93
	v_cvt_pk_bf16_f32 v93, v94, v95
	v_cvt_pk_bf16_f32 v94, v88, v89
	v_cvt_pk_bf16_f32 v95, v90, v91
	v_cvt_pk_bf16_f32 v84, v84, v85
	v_cvt_pk_bf16_f32 v85, v86, v87
	v_cvt_pk_bf16_f32 v86, v80, v81
	v_cvt_pk_bf16_f32 v87, v82, v83
	s_mul_i32 s20, s6, 64
	v_mov_b32_e32 v204, v92
	v_mov_b32_e32 v205, v93
	v_mov_b32_e32 v206, v94
	v_mov_b32_e32 v207, v95
	v_add_u32_e32 v208, s20, v144
	v_add_u32_e32 v209, s20, v145
	v_mov_b32_dpp v92, v84 row_ror:8 row_mask:0xf bank_mask:0xc
	v_mov_b32_dpp v93, v85 row_ror:8 row_mask:0xf bank_mask:0xc
	v_mov_b32_dpp v94, v86 row_ror:8 row_mask:0xf bank_mask:0xc
	v_mov_b32_dpp v95, v87 row_ror:8 row_mask:0xf bank_mask:0xc
	v_mov_b32_dpp v84, v204 row_ror:8 row_mask:0xf bank_mask:0x3
	v_mov_b32_dpp v85, v205 row_ror:8 row_mask:0xf bank_mask:0x3
	v_mov_b32_dpp v86, v206 row_ror:8 row_mask:0xf bank_mask:0x3
	v_mov_b32_dpp v87, v207 row_ror:8 row_mask:0xf bank_mask:0x3
	global_store_dwordx4 v208, v[92:95], s[24:25]
	global_store_dwordx4 v209, v[84:87], s[24:25]
	v_cvt_pk_bf16_f32 v76, v76, v77
	v_cvt_pk_bf16_f32 v77, v78, v79
	v_cvt_pk_bf16_f32 v78, v72, v73
	v_cvt_pk_bf16_f32 v79, v74, v75
	v_cvt_pk_bf16_f32 v68, v68, v69
	v_cvt_pk_bf16_f32 v69, v70, v71
	v_cvt_pk_bf16_f32 v70, v64, v65
	v_cvt_pk_bf16_f32 v71, v66, v67
	s_mul_i32 s20, s6, 96
	v_mov_b32_e32 v210, v76
	v_mov_b32_e32 v211, v77
	v_mov_b32_e32 v212, v78
	v_mov_b32_e32 v213, v79
	v_add_u32_e32 v214, s20, v144
	v_add_u32_e32 v215, s20, v145
	v_mov_b32_dpp v76, v68 row_ror:8 row_mask:0xf bank_mask:0xc
	v_mov_b32_dpp v77, v69 row_ror:8 row_mask:0xf bank_mask:0xc
	v_mov_b32_dpp v78, v70 row_ror:8 row_mask:0xf bank_mask:0xc
	v_mov_b32_dpp v79, v71 row_ror:8 row_mask:0xf bank_mask:0xc
	v_mov_b32_dpp v68, v210 row_ror:8 row_mask:0xf bank_mask:0x3
	v_mov_b32_dpp v69, v211 row_ror:8 row_mask:0xf bank_mask:0x3
	v_mov_b32_dpp v70, v212 row_ror:8 row_mask:0xf bank_mask:0x3
	v_mov_b32_dpp v71, v213 row_ror:8 row_mask:0xf bank_mask:0x3
	global_store_dwordx4 v214, v[76:79], s[24:25]
	global_store_dwordx4 v215, v[68:71], s[24:25]
	v_cvt_pk_bf16_f32 v60, v60, v61
	v_cvt_pk_bf16_f32 v61, v62, v63
	v_cvt_pk_bf16_f32 v62, v56, v57
	v_cvt_pk_bf16_f32 v63, v58, v59
	v_cvt_pk_bf16_f32 v52, v52, v53
	v_cvt_pk_bf16_f32 v53, v54, v55
	v_cvt_pk_bf16_f32 v54, v48, v49
	v_cvt_pk_bf16_f32 v55, v50, v51
	s_mul_i32 s20, s6, 256
	v_mov_b32_e32 v216, v60
	v_mov_b32_e32 v217, v61
	v_mov_b32_e32 v218, v62
	v_mov_b32_e32 v219, v63
	v_add_u32_e32 v220, s20, v144
	v_add_u32_e32 v221, s20, v145
	v_mov_b32_dpp v60, v52 row_ror:8 row_mask:0xf bank_mask:0xc
	v_mov_b32_dpp v61, v53 row_ror:8 row_mask:0xf bank_mask:0xc
	v_mov_b32_dpp v62, v54 row_ror:8 row_mask:0xf bank_mask:0xc
	v_mov_b32_dpp v63, v55 row_ror:8 row_mask:0xf bank_mask:0xc
	v_mov_b32_dpp v52, v216 row_ror:8 row_mask:0xf bank_mask:0x3
	v_mov_b32_dpp v53, v217 row_ror:8 row_mask:0xf bank_mask:0x3
	v_mov_b32_dpp v54, v218 row_ror:8 row_mask:0xf bank_mask:0x3
	v_mov_b32_dpp v55, v219 row_ror:8 row_mask:0xf bank_mask:0x3
	global_store_dwordx4 v220, v[60:63], s[24:25]
	global_store_dwordx4 v221, v[52:55], s[24:25]
	v_cvt_pk_bf16_f32 v44, v44, v45
	v_cvt_pk_bf16_f32 v45, v46, v47
	v_cvt_pk_bf16_f32 v46, v40, v41
	v_cvt_pk_bf16_f32 v47, v42, v43
	v_cvt_pk_bf16_f32 v36, v36, v37
	v_cvt_pk_bf16_f32 v37, v38, v39
	v_cvt_pk_bf16_f32 v38, v32, v33
	v_cvt_pk_bf16_f32 v39, v34, v35
	s_mul_i32 s20, s6, 288
	v_mov_b32_e32 v222, v44
	v_mov_b32_e32 v223, v45
	v_mov_b32_e32 v224, v46
	v_mov_b32_e32 v225, v47
	v_add_u32_e32 v226, s20, v144
	v_add_u32_e32 v227, s20, v145
	v_mov_b32_dpp v44, v36 row_ror:8 row_mask:0xf bank_mask:0xc
	v_mov_b32_dpp v45, v37 row_ror:8 row_mask:0xf bank_mask:0xc
	v_mov_b32_dpp v46, v38 row_ror:8 row_mask:0xf bank_mask:0xc
	v_mov_b32_dpp v47, v39 row_ror:8 row_mask:0xf bank_mask:0xc
	v_mov_b32_dpp v36, v222 row_ror:8 row_mask:0xf bank_mask:0x3
	v_mov_b32_dpp v37, v223 row_ror:8 row_mask:0xf bank_mask:0x3
	v_mov_b32_dpp v38, v224 row_ror:8 row_mask:0xf bank_mask:0x3
	v_mov_b32_dpp v39, v225 row_ror:8 row_mask:0xf bank_mask:0x3
	global_store_dwordx4 v226, v[44:47], s[24:25]
	global_store_dwordx4 v227, v[36:39], s[24:25]
	v_cvt_pk_bf16_f32 v28, v28, v29
	v_cvt_pk_bf16_f32 v29, v30, v31
	v_cvt_pk_bf16_f32 v30, v24, v25
	v_cvt_pk_bf16_f32 v31, v26, v27
	v_cvt_pk_bf16_f32 v20, v20, v21
	v_cvt_pk_bf16_f32 v21, v22, v23
	v_cvt_pk_bf16_f32 v22, v16, v17
	v_cvt_pk_bf16_f32 v23, v18, v19
	s_mul_i32 s20, s6, 320
	v_mov_b32_e32 v228, v28
	v_mov_b32_e32 v229, v29
	v_mov_b32_e32 v230, v30
	v_mov_b32_e32 v231, v31
	v_add_u32_e32 v232, s20, v144
	v_add_u32_e32 v233, s20, v145
	v_mov_b32_dpp v28, v20 row_ror:8 row_mask:0xf bank_mask:0xc
	v_mov_b32_dpp v29, v21 row_ror:8 row_mask:0xf bank_mask:0xc
	v_mov_b32_dpp v30, v22 row_ror:8 row_mask:0xf bank_mask:0xc
	v_mov_b32_dpp v31, v23 row_ror:8 row_mask:0xf bank_mask:0xc
	v_mov_b32_dpp v20, v228 row_ror:8 row_mask:0xf bank_mask:0x3
	v_mov_b32_dpp v21, v229 row_ror:8 row_mask:0xf bank_mask:0x3
	v_mov_b32_dpp v22, v230 row_ror:8 row_mask:0xf bank_mask:0x3
	v_mov_b32_dpp v23, v231 row_ror:8 row_mask:0xf bank_mask:0x3
	global_store_dwordx4 v232, v[28:31], s[24:25]
	global_store_dwordx4 v233, v[20:23], s[24:25]
	v_cvt_pk_bf16_f32 v12, v12, v13
	v_cvt_pk_bf16_f32 v13, v14, v15
	v_cvt_pk_bf16_f32 v14, v8, v9
	v_cvt_pk_bf16_f32 v15, v10, v11
	v_cvt_pk_bf16_f32 v4, v4, v5
	v_cvt_pk_bf16_f32 v5, v6, v7
	v_cvt_pk_bf16_f32 v6, v0, v1
	v_cvt_pk_bf16_f32 v7, v2, v3
	s_mul_i32 s20, s6, 352
	v_mov_b32_e32 v234, v12
	v_mov_b32_e32 v235, v13
	v_mov_b32_e32 v236, v14
	v_mov_b32_e32 v237, v15
	v_add_u32_e32 v238, s20, v144
	v_add_u32_e32 v239, s20, v145
	v_mov_b32_dpp v12, v4 row_ror:8 row_mask:0xf bank_mask:0xc
	v_mov_b32_dpp v13, v5 row_ror:8 row_mask:0xf bank_mask:0xc
	v_mov_b32_dpp v14, v6 row_ror:8 row_mask:0xf bank_mask:0xc
	v_mov_b32_dpp v15, v7 row_ror:8 row_mask:0xf bank_mask:0xc
	v_mov_b32_dpp v4, v234 row_ror:8 row_mask:0xf bank_mask:0x3
	v_mov_b32_dpp v5, v235 row_ror:8 row_mask:0xf bank_mask:0x3
	v_mov_b32_dpp v6, v236 row_ror:8 row_mask:0xf bank_mask:0x3
	v_mov_b32_dpp v7, v237 row_ror:8 row_mask:0xf bank_mask:0x3
	global_store_dwordx4 v238, v[12:15], s[24:25]
	global_store_dwordx4 v239, v[4:7], s[24:25]
	s_and_b64 vcc, exec, s[36:37]
	s_mov_b64 s[20:21], -1
	s_cbranch_vccnz .LBB0_662
	s_andn2_b64 vcc, exec, s[14:15]
	s_cbranch_vccnz .LBB0_661
	s_barrier
	s_branch .LBB0_661
